# v60 + embed row loop: 8 serialized load/cvt/store stages -> 8 loads in flight with counted waits
# speedup vs baseline: 1.0064x; 1.0015x over previous
; #define GAS __attribute__((address_space(1)))
; __device__ __forceinline__ unsigned cvt_pk_bf16(float lo, float hi) { unsigned r; asm volatile("v_cvt_pk_bf16_f32 %0, %1, %2" : "=v"(r) : "v"(lo), "v"(hi)); return r; }
; __device__ __forceinline__ float bf_lo(unsigned w) { return __uint_as_float(w << 16); }
; __device__ __forceinline__ float bf_hi(unsigned w) { return __uint_as_float(w & 0xffff0000u); }
; __device__ __forceinline__ void embed_phase(const Frame& F) {
;     ...
;     for (int r = F.gw; r < MT; r += F.NGW) {
;         const int seq = r < ROWS0 ? r / LP_P : NP + (r - ROWS0) / LP_S; const int t = row_tpos(r);
;         GAS u32x2* hp = (GAS u32x2*)(H + (size_t)r * D) + F.lane;
;         if (t < 0) {
; #pragma unroll
;             for (int j = 0; j < 8; ++j) hp[64 * j] = (u32x2){0u, 0u};
;             if (F.lane == 0) RS[r] = 0.f;
;             continue; }
;         const float* src = t < NMETA ? xm + (size_t)t * D : (seq < NP ? xp + ((size_t)seq * SP + (t - NMETA)) * D : xs + ((size_t)(seq - NP) * SS + (t - NMETA)) * D);
;         float ss = 0.f;
; #pragma unroll
;         for (int j = 0; j < 8; ++j) { const f32x4 v = __builtin_nontemporal_load((const GAS f32x4*)src + F.lane + 64 * j);
;             const unsigned w0 = cvt_pk_bf16(v[0], v[1]), w1 = cvt_pk_bf16(v[2], v[3]); hp[64 * j] = (u32x2){w0, w1};
;             const float a0 = bf_lo(w0), a1 = bf_hi(w0), a2 = bf_lo(w1), a3 = bf_hi(w1); ss += (a0 * a0 + a1 * a1) + (a2 * a2 + a3 * a3); }
;         const float rstd = 1.0f / sqrtf(wave_sum(ss) * (1.f / D) + NORM_EPS);
;         if (F.lane == 0) RS[r] = rstd;
.LBB0_41:
	s_mov_b32 s12, 0xd00000
	v_add_co_u32_e32 v14, vcc, s12, v4
	s_add_u32 s100, s36, 0x1000
	s_addc_u32 s101, s37, 0
	global_load_dwordx4 v[96:99], v192, s[36:37] nt
	global_load_dwordx4 v[100:103], v192, s[36:37] offset:1024 nt
	global_load_dwordx4 v[104:107], v192, s[36:37] offset:2048 nt
	global_load_dwordx4 v[108:111], v192, s[36:37] offset:3072 nt
	global_load_dwordx4 v[112:115], v192, s[100:101] nt
	global_load_dwordx4 v[116:119], v192, s[100:101] offset:1024 nt
	global_load_dwordx4 v[120:123], v192, s[100:101] offset:2048 nt
	global_load_dwordx4 v[124:127], v192, s[100:101] offset:3072 nt
	s_waitcnt vmcnt(7)
	v_cvt_pk_bf16_f32 v12, v96, v97
	v_cvt_pk_bf16_f32 v13, v98, v99
	global_store_dwordx2 v[6:7], v[12:13], off
	v_addc_co_u32_e32 v15, vcc, 0, v5, vcc
	s_waitcnt vmcnt(7)
	v_cvt_pk_bf16_f32 v18, v100, v101
	v_cvt_pk_bf16_f32 v19, v102, v103
	global_store_dwordx2 v[14:15], v[18:19], off offset:512
	v_lshl_add_u64 v[22:23], s[36:37], 0, v[192:193]
	s_movk_i32 s12, 0x1000
	s_waitcnt vmcnt(7)
	v_cvt_pk_bf16_f32 v20, v104, v105
	v_cvt_pk_bf16_f32 v21, v106, v107
	global_store_dwordx2 v[14:15], v[20:21], off offset:1024
	v_add_co_u32_e32 v22, vcc, s12, v22
	s_nop 0
	v_addc_co_u32_e32 v23, vcc, 0, v23, vcc
	s_waitcnt vmcnt(7)
	v_cvt_pk_bf16_f32 v26, v108, v109
	v_cvt_pk_bf16_f32 v27, v110, v111
	global_store_dwordx2 v[14:15], v[26:27], off offset:1536
	s_waitcnt vmcnt(7)
	v_cvt_pk_bf16_f32 v28, v112, v113
	v_cvt_pk_bf16_f32 v29, v114, v115
	global_store_dwordx2 v[14:15], v[28:29], off offset:2048
	s_waitcnt vmcnt(7)
	v_cvt_pk_bf16_f32 v30, v116, v117
	v_cvt_pk_bf16_f32 v31, v118, v119
	global_store_dwordx2 v[14:15], v[30:31], off offset:2560
	s_waitcnt vmcnt(7)
	v_cvt_pk_bf16_f32 v32, v120, v121
	v_cvt_pk_bf16_f32 v33, v122, v123
	global_store_dwordx2 v[14:15], v[32:33], off offset:3072
	v_lshlrev_b32_e32 v22, 16, v12
	v_and_b32_e32 v12, 0xffff0000, v12
	v_lshlrev_b32_e32 v23, 16, v13
	v_and_b32_e32 v13, 0xffff0000, v13
	v_mul_f32_e32 v12, v12, v12
	v_mul_f32_e32 v13, v13, v13
	v_fmac_f32_e32 v12, v22, v22
	v_fmac_f32_e32 v13, v23, v23
	v_add_f32_e32 v12, v12, v13
	v_lshlrev_b32_e32 v13, 16, v18
	v_and_b32_e32 v18, 0xffff0000, v18
	v_lshlrev_b32_e32 v22, 16, v19
	v_and_b32_e32 v19, 0xffff0000, v19
	v_mul_f32_e32 v18, v18, v18
	v_mul_f32_e32 v19, v19, v19
	v_fmac_f32_e32 v18, v13, v13
	v_fmac_f32_e32 v19, v22, v22
	v_add_f32_e32 v13, v18, v19
	v_add_f32_e32 v12, v12, v13
	v_lshlrev_b32_e32 v13, 16, v20
	v_and_b32_e32 v18, 0xffff0000, v20
	v_and_b32_e32 v20, 0xffff0000, v21
	v_lshlrev_b32_e32 v19, 16, v21
	v_mul_f32_e32 v18, v18, v18
	v_mul_f32_e32 v20, v20, v20
	v_fmac_f32_e32 v18, v13, v13
	v_fmac_f32_e32 v20, v19, v19
	v_add_f32_e32 v13, v18, v20
	v_and_b32_e32 v18, 0xffff0000, v26
	v_and_b32_e32 v20, 0xffff0000, v27
	v_add_f32_e32 v12, v12, v13
	v_lshlrev_b32_e32 v13, 16, v26
	v_lshlrev_b32_e32 v19, 16, v27
	v_mul_f32_e32 v18, v18, v18
	v_mul_f32_e32 v20, v20, v20
	v_fmac_f32_e32 v18, v13, v13
	v_fmac_f32_e32 v20, v19, v19
	v_add_f32_e32 v13, v18, v20
	v_and_b32_e32 v18, 0xffff0000, v28
	v_and_b32_e32 v20, 0xffff0000, v29
	v_add_f32_e32 v12, v12, v13
	v_lshlrev_b32_e32 v13, 16, v28
	v_lshlrev_b32_e32 v19, 16, v29
	v_mul_f32_e32 v18, v18, v18
	v_mul_f32_e32 v20, v20, v20
	v_fmac_f32_e32 v18, v13, v13
	v_fmac_f32_e32 v20, v19, v19
	v_add_f32_e32 v13, v18, v20
	v_and_b32_e32 v18, 0xffff0000, v30
	v_and_b32_e32 v20, 0xffff0000, v31
	v_add_f32_e32 v12, v12, v13
	v_lshlrev_b32_e32 v13, 16, v30
	v_lshlrev_b32_e32 v19, 16, v31
	v_mul_f32_e32 v18, v18, v18
	v_mul_f32_e32 v20, v20, v20
	v_fmac_f32_e32 v18, v13, v13
	v_fmac_f32_e32 v20, v19, v19
	v_add_f32_e32 v13, v18, v20
	v_and_b32_e32 v18, 0xffff0000, v32
	v_and_b32_e32 v20, 0xffff0000, v33
	v_add_f32_e32 v12, v12, v13
	v_lshlrev_b32_e32 v13, 16, v32
	v_lshlrev_b32_e32 v19, 16, v33
	v_mul_f32_e32 v18, v18, v18
	v_mul_f32_e32 v20, v20, v20
	v_fmac_f32_e32 v18, v13, v13
	v_fmac_f32_e32 v20, v19, v19
	v_add_f32_e32 v13, v18, v20
	s_waitcnt vmcnt(7)
	v_cvt_pk_bf16_f32 v8, v124, v125
	v_cvt_pk_bf16_f32 v9, v126, v127
	v_add_f32_e32 v12, v12, v13
	v_and_b32_e32 v11, 0xffff0000, v8
	v_and_b32_e32 v18, 0xffff0000, v9
	v_lshlrev_b32_e32 v10, 16, v8
	v_lshlrev_b32_e32 v13, 16, v9
	v_mul_f32_e32 v11, v11, v11
	v_mul_f32_e32 v18, v18, v18
	v_fmac_f32_e32 v11, v10, v10
	v_fmac_f32_e32 v18, v13, v13
	v_add_f32_e32 v10, v11, v18
	v_add_f32_e32 v10, v12, v10
	ds_swizzle_b32 v11, v10 offset:swizzle(SWAP,1)
	global_store_dwordx2 v[14:15], v[8:9], off offset:3584
	s_mov_b64 s[40:41], 0
	s_mov_b64 s[38:39], 0
	s_waitcnt lgkmcnt(0)
	v_add_f32_e32 v10, v10, v11
	ds_swizzle_b32 v11, v10 offset:swizzle(SWAP,2)
	s_waitcnt lgkmcnt(0)
	v_add_f32_e32 v10, v10, v11
	ds_swizzle_b32 v11, v10 offset:swizzle(SWAP,4)
	s_waitcnt lgkmcnt(0)
	v_add_f32_e32 v10, v10, v11
	ds_swizzle_b32 v11, v10 offset:swizzle(SWAP,8)
	s_waitcnt lgkmcnt(0)
	v_add_f32_e32 v10, v10, v11
	ds_swizzle_b32 v11, v10 offset:swizzle(SWAP,16)
	s_waitcnt lgkmcnt(0)
	v_add_f32_e32 v9, v10, v11
	v_mov_b32_e32 v10, v9
	s_nop 1
	v_permlane32_swap_b32_e32 v9, v10
	s_and_saveexec_b64 s[12:13], s[34:35]
	s_xor_b64 s[42:43], exec, s[12:13]
	s_cbranch_execz .LBB0_43
	v_add_f32_e32 v8, v9, v10
	v_fmamk_f32 v8, v8, 0x3a000000, v250
	s_mov_b32 s12, 0xf800000
	v_mul_f32_e32 v9, 0x4f800000, v8
	v_cmp_gt_f32_e32 vcc, s12, v8
	s_mov_b64 s[38:39], exec
	s_nop 0
	v_cndmask_b32_e32 v8, v8, v9, vcc
	v_sqrt_f32_e32 v9, v8
	s_nop 0
	v_add_u32_e32 v10, -1, v9
	v_fma_f32 v11, -v10, v9, v8
	v_cmp_ge_f32_e64 s[36:37], 0, v11
	v_add_u32_e32 v11, 1, v9
	s_nop 0
	v_cndmask_b32_e64 v10, v9, v10, s[36:37]
	v_fma_f32 v9, -v11, v9, v8
	v_cmp_lt_f32_e64 s[36:37], 0, v9
	s_nop 1
	v_cndmask_b32_e64 v9, v10, v11, s[36:37]
	v_mul_f32_e32 v10, 0x37800000, v9
	v_cndmask_b32_e32 v9, v9, v10, vcc
	v_cmp_class_f32_e32 vcc, v8, v251
	s_nop 1
	v_cndmask_b32_e32 v8, v9, v8, vcc
	v_div_scale_f32 v9, s[12:13], v8, v8, 1.0
	v_rcp_f32_e32 v10, v9
	s_nop 0
	v_fma_f32 v11, -v9, v10, 1.0
	v_fmac_f32_e32 v10, v11, v10
	v_div_scale_f32 v11, vcc, 1.0, v8, 1.0
	v_mul_f32_e32 v12, v11, v10
	v_fma_f32 v13, -v9, v12, v11
	v_fmac_f32_e32 v12, v13, v10
	v_fma_f32 v9, -v9, v12, v11
	v_div_fmas_f32 v9, v9, v10, v12
	v_div_fixup_f32 v8, v9, v8, 1.0
